# FFN_IN GEMM: tile remap for L2 locality + new k-loop (register-staged frags, DMA for tile k+2 interleaved with MFMAs, SGPR-base DMA addressing)
# speedup vs baseline: 1.2851x; 1.0657x over previous
.LBB0_755:
	s_and_b32 s58, s3, 7
	s_lshl_b32 s58, s58, 4
	s_bfe_u32 s59, s3, 0x60003
	s_lshr_b32 s4, s3, 9
	s_cmp_lt_u32 s4, 10
	s_cbranch_scc0 .Lmap_tail_0
	s_cmp_gt_u32 s4, 4
	s_cselect_b32 s76, 5, 0
	s_cselect_b32 s63, 8, 0
	s_sub_u32 s4, s4, s76
	s_lshl_b32 s4, s4, 3
	s_lshr_b32 s76, s59, 3
	s_add_u32 s76, s76, s4
	s_and_b32 s59, s59, 7
	s_add_u32 s4, s58, s63
	s_add_u32 s4, s4, s59
	s_branch .Lmap_done_0
.Lmap_tail_0:
	s_lshr_b32 s76, s59, 4
	s_add_u32 s76, s76, 40
	s_and_b32 s59, s59, 15
	s_add_u32 s4, s58, s59
.Lmap_done_0:
	s_lshl_b32 s60, s4, 7
	s_lshl_b32 s58, s76, 7
	s_ashr_i32 s61, s60, 31
	s_ashr_i32 s59, s58, 31
	s_lshl_b64 s[62:63], s[60:61], 11
	s_lshl_b64 s[64:65], s[58:59], 11
	s_lshl_b32 s59, s60, 11
	s_add_u32 s18, s14, s59
	s_addc_u32 s19, s15, 0
	s_add_u32 s18, s18, 0x679f000
	s_addc_u32 s19, s19, 0
	s_add_u32 s20, s18, 0x10000
	s_addc_u32 s21, s19, 0
	s_add_u32 s22, s20, 0x10000
	s_addc_u32 s23, s21, 0
	s_add_u32 s24, s22, 0x10000
	s_addc_u32 s25, s23, 0
	s_lshl_b32 s59, s58, 11
	s_add_u32 s26, s14, s59
	s_addc_u32 s27, s15, 0
	s_add_u32 s26, s26, 0x19a0000
	s_addc_u32 s27, s27, 0
	s_add_u32 s28, s26, 0x10000
	s_addc_u32 s29, s27, 0
	s_add_u32 s30, s28, 0x10000
	s_addc_u32 s31, s29, 0
	s_add_u32 s34, s30, 0x10000
	s_addc_u32 s35, s31, 0
	v_readfirstlane_b32 s36, v94
	v_mov_b32_e32 v254, v76
	s_mov_b32 m0, s36
	s_nop 0
	global_load_lds_dwordx4 v254, s[18:19]
	s_add_u32 m0, m0, 0x1000
	s_nop 0
	global_load_lds_dwordx4 v254, s[20:21]
	s_add_u32 m0, m0, 0x1000
	s_nop 0
	global_load_lds_dwordx4 v254, s[22:23]
	s_add_u32 m0, m0, 0x1000
	s_nop 0
	global_load_lds_dwordx4 v254, s[24:25]
	s_add_u32 m0, m0, 0x1000
	s_nop 0
	global_load_lds_dwordx4 v254, s[26:27]
	s_add_u32 m0, m0, 0x1000
	s_nop 0
	global_load_lds_dwordx4 v254, s[28:29]
	s_add_u32 m0, m0, 0x1000
	s_nop 0
	global_load_lds_dwordx4 v254, s[30:31]
	s_add_u32 m0, m0, 0x1000
	s_nop 0
	global_load_lds_dwordx4 v254, s[34:35]
	v_add_u32_e32 v254, 0x80, v254
	s_add_u32 m0, s36, 0x8000
	s_nop 0
	global_load_lds_dwordx4 v254, s[18:19]
	s_add_u32 m0, m0, 0x1000
	s_nop 0
	global_load_lds_dwordx4 v254, s[20:21]
	s_add_u32 m0, m0, 0x1000
	s_nop 0
	global_load_lds_dwordx4 v254, s[22:23]
	s_add_u32 m0, m0, 0x1000
	s_nop 0
	global_load_lds_dwordx4 v254, s[24:25]
	s_add_u32 m0, m0, 0x1000
	s_nop 0
	global_load_lds_dwordx4 v254, s[26:27]
	s_add_u32 m0, m0, 0x1000
	s_nop 0
	global_load_lds_dwordx4 v254, s[28:29]
	s_add_u32 m0, m0, 0x1000
	s_nop 0
	global_load_lds_dwordx4 v254, s[30:31]
	s_add_u32 m0, m0, 0x1000
	s_nop 0
	global_load_lds_dwordx4 v254, s[34:35]
	v_add_u32_e32 v254, 0x80, v254
	v_mov_b32_e32 v48, 0
	v_mov_b32_e32 v49, 0
	v_mov_b32_e32 v50, 0
	v_mov_b32_e32 v51, 0
	v_mov_b32_e32 v52, 0
	v_mov_b32_e32 v53, 0
	v_mov_b32_e32 v54, 0
	v_mov_b32_e32 v55, 0
	v_mov_b32_e32 v56, 0
	v_mov_b32_e32 v57, 0
	v_mov_b32_e32 v58, 0
	v_mov_b32_e32 v59, 0
	v_mov_b32_e32 v60, 0
	v_mov_b32_e32 v61, 0
	v_mov_b32_e32 v62, 0
	v_mov_b32_e32 v63, 0
	v_mov_b32_e32 v32, 0
	v_mov_b32_e32 v33, 0
	v_mov_b32_e32 v34, 0
	v_mov_b32_e32 v35, 0
	v_mov_b32_e32 v36, 0
	v_mov_b32_e32 v37, 0
	v_mov_b32_e32 v38, 0
	v_mov_b32_e32 v39, 0
	v_mov_b32_e32 v40, 0
	v_mov_b32_e32 v41, 0
	v_mov_b32_e32 v42, 0
	v_mov_b32_e32 v43, 0
	v_mov_b32_e32 v44, 0
	v_mov_b32_e32 v45, 0
	v_mov_b32_e32 v46, 0
	v_mov_b32_e32 v47, 0
	v_mov_b32_e32 v16, 0
	v_mov_b32_e32 v17, 0
	v_mov_b32_e32 v18, 0
	v_mov_b32_e32 v19, 0
	v_mov_b32_e32 v20, 0
	v_mov_b32_e32 v21, 0
	v_mov_b32_e32 v22, 0
	v_mov_b32_e32 v23, 0
	v_mov_b32_e32 v24, 0
	v_mov_b32_e32 v25, 0
	v_mov_b32_e32 v26, 0
	v_mov_b32_e32 v27, 0
	v_mov_b32_e32 v28, 0
	v_mov_b32_e32 v29, 0
	v_mov_b32_e32 v30, 0
	v_mov_b32_e32 v31, 0
	v_mov_b32_e32 v0, 0
	v_mov_b32_e32 v1, 0
	v_mov_b32_e32 v2, 0
	v_mov_b32_e32 v3, 0
	v_mov_b32_e32 v4, 0
	v_mov_b32_e32 v5, 0
	v_mov_b32_e32 v6, 0
	v_mov_b32_e32 v7, 0
	v_mov_b32_e32 v8, 0
	v_mov_b32_e32 v9, 0
	v_mov_b32_e32 v10, 0
	v_mov_b32_e32 v11, 0
	v_mov_b32_e32 v12, 0
	v_mov_b32_e32 v13, 0
	v_mov_b32_e32 v14, 0
	v_mov_b32_e32 v15, 0
	s_mov_b32 s37, 7
.Lgk_loop_p7:
	s_waitcnt vmcnt(8)
	s_barrier
	ds_read_b128 v[64:67], v110
	ds_read_b128 v[68:71], v111 offset:16384
	ds_read_b128 v[72:75], v111 offset:20480
	ds_read_b128 v[82:85], v111 offset:24576
	ds_read_b128 v[86:89], v111 offset:28672
	ds_read_b128 v[120:123], v112
	ds_read_b128 v[124:127], v113 offset:16384
	ds_read_b128 v[128:131], v113 offset:20480
	ds_read_b128 v[132:135], v113 offset:24576
	ds_read_b128 v[136:139], v113 offset:28672
	ds_read_b128 v[140:143], v114
	ds_read_b128 v[218:221], v115 offset:16384
	ds_read_b128 v[222:225], v115 offset:20480
	ds_read_b128 v[226:229], v115 offset:24576
	ds_read_b128 v[230:233], v115 offset:28672
	ds_read_b128 v[234:237], v116
	ds_read_b128 v[238:241], v117 offset:16384
	ds_read_b128 v[242:245], v117 offset:20480
	ds_read_b128 v[246:249], v117 offset:24576
	ds_read_b128 v[250:253], v117 offset:28672
	s_waitcnt lgkmcnt(0)
	s_barrier
	s_mov_b32 m0, s36
	s_setprio 1
	v_mfma_f32_32x32x16_bf16 v[48:63], v[64:67], v[68:71], v[48:63]
	v_mfma_f32_32x32x16_bf16 v[32:47], v[64:67], v[72:75], v[32:47]
	global_load_lds_dwordx4 v254, s[18:19]
	s_add_u32 m0, m0, 0x1000
	v_mfma_f32_32x32x16_bf16 v[16:31], v[64:67], v[82:85], v[16:31]
	v_mfma_f32_32x32x16_bf16 v[0:15], v[64:67], v[86:89], v[0:15]
	global_load_lds_dwordx4 v254, s[20:21]
	s_add_u32 m0, m0, 0x1000
	v_mfma_f32_32x32x16_bf16 v[48:63], v[120:123], v[124:127], v[48:63]
	v_mfma_f32_32x32x16_bf16 v[32:47], v[120:123], v[128:131], v[32:47]
	global_load_lds_dwordx4 v254, s[22:23]
	s_add_u32 m0, m0, 0x1000
	v_mfma_f32_32x32x16_bf16 v[16:31], v[120:123], v[132:135], v[16:31]
	v_mfma_f32_32x32x16_bf16 v[0:15], v[120:123], v[136:139], v[0:15]
	global_load_lds_dwordx4 v254, s[24:25]
	s_add_u32 m0, m0, 0x1000
	v_mfma_f32_32x32x16_bf16 v[48:63], v[140:143], v[218:221], v[48:63]
	v_mfma_f32_32x32x16_bf16 v[32:47], v[140:143], v[222:225], v[32:47]
	global_load_lds_dwordx4 v254, s[26:27]
	s_add_u32 m0, m0, 0x1000
	v_mfma_f32_32x32x16_bf16 v[16:31], v[140:143], v[226:229], v[16:31]
	v_mfma_f32_32x32x16_bf16 v[0:15], v[140:143], v[230:233], v[0:15]
	global_load_lds_dwordx4 v254, s[28:29]
	s_add_u32 m0, m0, 0x1000
	v_mfma_f32_32x32x16_bf16 v[48:63], v[234:237], v[238:241], v[48:63]
	v_mfma_f32_32x32x16_bf16 v[32:47], v[234:237], v[242:245], v[32:47]
	global_load_lds_dwordx4 v254, s[30:31]
	s_add_u32 m0, m0, 0x1000
	v_mfma_f32_32x32x16_bf16 v[16:31], v[234:237], v[246:249], v[16:31]
	v_mfma_f32_32x32x16_bf16 v[0:15], v[234:237], v[250:253], v[0:15]
	global_load_lds_dwordx4 v254, s[34:35]
	s_setprio 0
	v_add_u32_e32 v254, 0x80, v254
	s_waitcnt vmcnt(8)
	s_barrier
	ds_read_b128 v[64:67], v110 offset:32768
	ds_read_b128 v[68:71], v111 offset:49152
	ds_read_b128 v[72:75], v111 offset:53248
	ds_read_b128 v[82:85], v111 offset:57344
	ds_read_b128 v[86:89], v111 offset:61440
	ds_read_b128 v[120:123], v112 offset:32768
	ds_read_b128 v[124:127], v113 offset:49152
	ds_read_b128 v[128:131], v113 offset:53248
	ds_read_b128 v[132:135], v113 offset:57344
	ds_read_b128 v[136:139], v113 offset:61440
	ds_read_b128 v[140:143], v114 offset:32768
	ds_read_b128 v[218:221], v115 offset:49152
	ds_read_b128 v[222:225], v115 offset:53248
	ds_read_b128 v[226:229], v115 offset:57344
	ds_read_b128 v[230:233], v115 offset:61440
	ds_read_b128 v[234:237], v116 offset:32768
	ds_read_b128 v[238:241], v117 offset:49152
	ds_read_b128 v[242:245], v117 offset:53248
	ds_read_b128 v[246:249], v117 offset:57344
	ds_read_b128 v[250:253], v117 offset:61440
	s_waitcnt lgkmcnt(0)
	s_barrier
	s_add_u32 m0, s36, 0x8000
	s_setprio 1
	v_mfma_f32_32x32x16_bf16 v[48:63], v[64:67], v[68:71], v[48:63]
	v_mfma_f32_32x32x16_bf16 v[32:47], v[64:67], v[72:75], v[32:47]
	global_load_lds_dwordx4 v254, s[18:19]
	s_add_u32 m0, m0, 0x1000
	v_mfma_f32_32x32x16_bf16 v[16:31], v[64:67], v[82:85], v[16:31]
	v_mfma_f32_32x32x16_bf16 v[0:15], v[64:67], v[86:89], v[0:15]
	global_load_lds_dwordx4 v254, s[20:21]
	s_add_u32 m0, m0, 0x1000
	v_mfma_f32_32x32x16_bf16 v[48:63], v[120:123], v[124:127], v[48:63]
	v_mfma_f32_32x32x16_bf16 v[32:47], v[120:123], v[128:131], v[32:47]
	global_load_lds_dwordx4 v254, s[22:23]
	s_add_u32 m0, m0, 0x1000
	v_mfma_f32_32x32x16_bf16 v[16:31], v[120:123], v[132:135], v[16:31]
	v_mfma_f32_32x32x16_bf16 v[0:15], v[120:123], v[136:139], v[0:15]
	global_load_lds_dwordx4 v254, s[24:25]
	s_add_u32 m0, m0, 0x1000
	v_mfma_f32_32x32x16_bf16 v[48:63], v[140:143], v[218:221], v[48:63]
	v_mfma_f32_32x32x16_bf16 v[32:47], v[140:143], v[222:225], v[32:47]
	global_load_lds_dwordx4 v254, s[26:27]
	s_add_u32 m0, m0, 0x1000
	v_mfma_f32_32x32x16_bf16 v[16:31], v[140:143], v[226:229], v[16:31]
	v_mfma_f32_32x32x16_bf16 v[0:15], v[140:143], v[230:233], v[0:15]
	global_load_lds_dwordx4 v254, s[28:29]
	s_add_u32 m0, m0, 0x1000
	v_mfma_f32_32x32x16_bf16 v[48:63], v[234:237], v[238:241], v[48:63]
	v_mfma_f32_32x32x16_bf16 v[32:47], v[234:237], v[242:245], v[32:47]
	global_load_lds_dwordx4 v254, s[30:31]
	s_add_u32 m0, m0, 0x1000
	v_mfma_f32_32x32x16_bf16 v[16:31], v[234:237], v[246:249], v[16:31]
	v_mfma_f32_32x32x16_bf16 v[0:15], v[234:237], v[250:253], v[0:15]
	global_load_lds_dwordx4 v254, s[34:35]
	s_setprio 0
	v_add_u32_e32 v254, 0x80, v254
	s_sub_u32 s37, s37, 1
	s_cmp_lg_u32 s37, 0
	s_cbranch_scc1 .Lgk_loop_p7
	s_waitcnt vmcnt(8)
	s_barrier
	ds_read_b128 v[64:67], v110
	ds_read_b128 v[68:71], v111 offset:16384
	ds_read_b128 v[72:75], v111 offset:20480
	ds_read_b128 v[82:85], v111 offset:24576
	ds_read_b128 v[86:89], v111 offset:28672
	ds_read_b128 v[120:123], v112
	ds_read_b128 v[124:127], v113 offset:16384
	ds_read_b128 v[128:131], v113 offset:20480
	ds_read_b128 v[132:135], v113 offset:24576
	ds_read_b128 v[136:139], v113 offset:28672
	ds_read_b128 v[140:143], v114
	ds_read_b128 v[218:221], v115 offset:16384
	ds_read_b128 v[222:225], v115 offset:20480
	ds_read_b128 v[226:229], v115 offset:24576
	ds_read_b128 v[230:233], v115 offset:28672
	ds_read_b128 v[234:237], v116
	ds_read_b128 v[238:241], v117 offset:16384
	ds_read_b128 v[242:245], v117 offset:20480
	ds_read_b128 v[246:249], v117 offset:24576
	ds_read_b128 v[250:253], v117 offset:28672
	s_waitcnt lgkmcnt(0)
	s_barrier
	s_setprio 1
	v_mfma_f32_32x32x16_bf16 v[48:63], v[64:67], v[68:71], v[48:63]
	v_mfma_f32_32x32x16_bf16 v[32:47], v[64:67], v[72:75], v[32:47]
	v_mfma_f32_32x32x16_bf16 v[16:31], v[64:67], v[82:85], v[16:31]
	v_mfma_f32_32x32x16_bf16 v[0:15], v[64:67], v[86:89], v[0:15]
	v_mfma_f32_32x32x16_bf16 v[48:63], v[120:123], v[124:127], v[48:63]
	v_mfma_f32_32x32x16_bf16 v[32:47], v[120:123], v[128:131], v[32:47]
	v_mfma_f32_32x32x16_bf16 v[16:31], v[120:123], v[132:135], v[16:31]
	v_mfma_f32_32x32x16_bf16 v[0:15], v[120:123], v[136:139], v[0:15]
	v_mfma_f32_32x32x16_bf16 v[48:63], v[140:143], v[218:221], v[48:63]
	v_mfma_f32_32x32x16_bf16 v[32:47], v[140:143], v[222:225], v[32:47]
	v_mfma_f32_32x32x16_bf16 v[16:31], v[140:143], v[226:229], v[16:31]
	v_mfma_f32_32x32x16_bf16 v[0:15], v[140:143], v[230:233], v[0:15]
	v_mfma_f32_32x32x16_bf16 v[48:63], v[234:237], v[238:241], v[48:63]
	v_mfma_f32_32x32x16_bf16 v[32:47], v[234:237], v[242:245], v[32:47]
	v_mfma_f32_32x32x16_bf16 v[16:31], v[234:237], v[246:249], v[16:31]
	v_mfma_f32_32x32x16_bf16 v[0:15], v[234:237], v[250:253], v[0:15]
	s_setprio 0
	s_waitcnt vmcnt(0)
	s_barrier
	ds_read_b128 v[64:67], v110 offset:32768
	ds_read_b128 v[68:71], v111 offset:49152
	ds_read_b128 v[72:75], v111 offset:53248
	ds_read_b128 v[82:85], v111 offset:57344
	ds_read_b128 v[86:89], v111 offset:61440
	ds_read_b128 v[120:123], v112 offset:32768
	ds_read_b128 v[124:127], v113 offset:49152
	ds_read_b128 v[128:131], v113 offset:53248
	ds_read_b128 v[132:135], v113 offset:57344
	ds_read_b128 v[136:139], v113 offset:61440
	ds_read_b128 v[140:143], v114 offset:32768
	ds_read_b128 v[218:221], v115 offset:49152
	ds_read_b128 v[222:225], v115 offset:53248
	ds_read_b128 v[226:229], v115 offset:57344
	ds_read_b128 v[230:233], v115 offset:61440
	ds_read_b128 v[234:237], v116 offset:32768
	ds_read_b128 v[238:241], v117 offset:49152
	ds_read_b128 v[242:245], v117 offset:53248
	ds_read_b128 v[246:249], v117 offset:57344
	ds_read_b128 v[250:253], v117 offset:61440
	s_waitcnt lgkmcnt(0)
	s_barrier
	s_setprio 1
	v_mfma_f32_32x32x16_bf16 v[48:63], v[64:67], v[68:71], v[48:63]
	v_mfma_f32_32x32x16_bf16 v[32:47], v[64:67], v[72:75], v[32:47]
	v_mfma_f32_32x32x16_bf16 v[16:31], v[64:67], v[82:85], v[16:31]
	v_mfma_f32_32x32x16_bf16 v[0:15], v[64:67], v[86:89], v[0:15]
	v_mfma_f32_32x32x16_bf16 v[48:63], v[120:123], v[124:127], v[48:63]
	v_mfma_f32_32x32x16_bf16 v[32:47], v[120:123], v[128:131], v[32:47]
	v_mfma_f32_32x32x16_bf16 v[16:31], v[120:123], v[132:135], v[16:31]
	v_mfma_f32_32x32x16_bf16 v[0:15], v[120:123], v[136:139], v[0:15]
	v_mfma_f32_32x32x16_bf16 v[48:63], v[140:143], v[218:221], v[48:63]
	v_mfma_f32_32x32x16_bf16 v[32:47], v[140:143], v[222:225], v[32:47]
	v_mfma_f32_32x32x16_bf16 v[16:31], v[140:143], v[226:229], v[16:31]
	v_mfma_f32_32x32x16_bf16 v[0:15], v[140:143], v[230:233], v[0:15]
	v_mfma_f32_32x32x16_bf16 v[48:63], v[234:237], v[238:241], v[48:63]
	v_mfma_f32_32x32x16_bf16 v[32:47], v[234:237], v[242:245], v[32:47]
	v_mfma_f32_32x32x16_bf16 v[16:31], v[234:237], v[246:249], v[16:31]
	v_mfma_f32_32x32x16_bf16 v[0:15], v[234:237], v[250:253], v[0:15]
	s_setprio 0
	s_branch .LBB0_754

.Lmap_done_1:
	s_lshl_b32 s60, s4, 7
	s_lshl_b32 s58, s76, 7
	s_ashr_i32 s61, s60, 31
	s_ashr_i32 s59, s58, 31
	s_lshl_b64 s[62:63], s[60:61], 11
	s_lshl_b64 s[64:65], s[58:59], 11
	s_lshl_b32 s59, s60, 11
	s_add_u32 s18, s14, s59
	s_addc_u32 s19, s15, 0
	s_add_u32 s18, s18, 0x679f000
	s_addc_u32 s19, s19, 0
	s_add_u32 s20, s18, 0x10000
	s_addc_u32 s21, s19, 0
	s_add_u32 s22, s20, 0x10000
	s_addc_u32 s23, s21, 0
	s_add_u32 s24, s22, 0x10000
	s_addc_u32 s25, s23, 0
	s_lshl_b32 s59, s58, 11
	s_add_u32 s26, s14, s59
	s_addc_u32 s27, s15, 0
	s_add_u32 s26, s26, 0x24a0000
	s_addc_u32 s27, s27, 0
	s_add_u32 s28, s26, 0x10000
	s_addc_u32 s29, s27, 0
	s_add_u32 s30, s28, 0x10000
	s_addc_u32 s31, s29, 0
	s_add_u32 s34, s30, 0x10000
	s_addc_u32 s35, s31, 0
	v_readfirstlane_b32 s36, v94
	v_mov_b32_e32 v254, v76
	s_mov_b32 m0, s36
	s_nop 0
	global_load_lds_dwordx4 v254, s[18:19]
	s_add_u32 m0, m0, 0x1000
	s_nop 0
	global_load_lds_dwordx4 v254, s[20:21]
	s_add_u32 m0, m0, 0x1000
	s_nop 0
	global_load_lds_dwordx4 v254, s[22:23]
	s_add_u32 m0, m0, 0x1000
	s_nop 0
	global_load_lds_dwordx4 v254, s[24:25]
	s_add_u32 m0, m0, 0x1000
	s_nop 0
	global_load_lds_dwordx4 v254, s[26:27]
	s_add_u32 m0, m0, 0x1000
	s_nop 0
	global_load_lds_dwordx4 v254, s[28:29]
	s_add_u32 m0, m0, 0x1000
	s_nop 0
	global_load_lds_dwordx4 v254, s[30:31]
	s_add_u32 m0, m0, 0x1000
	s_nop 0
	global_load_lds_dwordx4 v254, s[34:35]
	v_add_u32_e32 v254, 0x80, v254
	s_add_u32 m0, s36, 0x8000
	s_nop 0
	global_load_lds_dwordx4 v254, s[18:19]
	s_add_u32 m0, m0, 0x1000
	s_nop 0
	global_load_lds_dwordx4 v254, s[20:21]
	s_add_u32 m0, m0, 0x1000
	s_nop 0
	global_load_lds_dwordx4 v254, s[22:23]
	s_add_u32 m0, m0, 0x1000
	s_nop 0
	global_load_lds_dwordx4 v254, s[24:25]
	s_add_u32 m0, m0, 0x1000
	s_nop 0
	global_load_lds_dwordx4 v254, s[26:27]
	s_add_u32 m0, m0, 0x1000
	s_nop 0
	global_load_lds_dwordx4 v254, s[28:29]
	s_add_u32 m0, m0, 0x1000
	s_nop 0
	global_load_lds_dwordx4 v254, s[30:31]
	s_add_u32 m0, m0, 0x1000
	s_nop 0
	global_load_lds_dwordx4 v254, s[34:35]
	v_add_u32_e32 v254, 0x80, v254
	v_mov_b32_e32 v48, 0
	v_mov_b32_e32 v49, 0
	v_mov_b32_e32 v50, 0
	v_mov_b32_e32 v51, 0
	v_mov_b32_e32 v52, 0
	v_mov_b32_e32 v53, 0
	v_mov_b32_e32 v54, 0
	v_mov_b32_e32 v55, 0
	v_mov_b32_e32 v56, 0
	v_mov_b32_e32 v57, 0
	v_mov_b32_e32 v58, 0
	v_mov_b32_e32 v59, 0
	v_mov_b32_e32 v60, 0
	v_mov_b32_e32 v61, 0
	v_mov_b32_e32 v62, 0
	v_mov_b32_e32 v63, 0
	v_mov_b32_e32 v32, 0
	v_mov_b32_e32 v33, 0
	v_mov_b32_e32 v34, 0
	v_mov_b32_e32 v35, 0
	v_mov_b32_e32 v36, 0
	v_mov_b32_e32 v37, 0
	v_mov_b32_e32 v38, 0
	v_mov_b32_e32 v39, 0
	v_mov_b32_e32 v40, 0
	v_mov_b32_e32 v41, 0
	v_mov_b32_e32 v42, 0
	v_mov_b32_e32 v43, 0
	v_mov_b32_e32 v44, 0
	v_mov_b32_e32 v45, 0
	v_mov_b32_e32 v46, 0
	v_mov_b32_e32 v47, 0
	v_mov_b32_e32 v16, 0
	v_mov_b32_e32 v17, 0
	v_mov_b32_e32 v18, 0
	v_mov_b32_e32 v19, 0
	v_mov_b32_e32 v20, 0
	v_mov_b32_e32 v21, 0
	v_mov_b32_e32 v22, 0
	v_mov_b32_e32 v23, 0
	v_mov_b32_e32 v24, 0
	v_mov_b32_e32 v25, 0
	v_mov_b32_e32 v26, 0
	v_mov_b32_e32 v27, 0
	v_mov_b32_e32 v28, 0
	v_mov_b32_e32 v29, 0
	v_mov_b32_e32 v30, 0
	v_mov_b32_e32 v31, 0
	v_mov_b32_e32 v0, 0
	v_mov_b32_e32 v1, 0
	v_mov_b32_e32 v2, 0
	v_mov_b32_e32 v3, 0
	v_mov_b32_e32 v4, 0
	v_mov_b32_e32 v5, 0
	v_mov_b32_e32 v6, 0
	v_mov_b32_e32 v7, 0
	v_mov_b32_e32 v8, 0
	v_mov_b32_e32 v9, 0
	v_mov_b32_e32 v10, 0
	v_mov_b32_e32 v11, 0
	v_mov_b32_e32 v12, 0
	v_mov_b32_e32 v13, 0
	v_mov_b32_e32 v14, 0
	v_mov_b32_e32 v15, 0
	s_mov_b32 s37, 7

.Lmap_done_2:
	s_lshl_b32 s60, s4, 7
	s_lshl_b32 s58, s76, 7
	s_ashr_i32 s61, s60, 31
	s_ashr_i32 s59, s58, 31
	s_lshl_b64 s[62:63], s[60:61], 11
	s_lshl_b64 s[64:65], s[58:59], 11
	s_lshl_b32 s59, s60, 11
	s_add_u32 s18, s14, s59
	s_addc_u32 s19, s15, 0
	s_add_u32 s18, s18, 0x679f000
	s_addc_u32 s19, s19, 0
	s_add_u32 s20, s18, 0x10000
	s_addc_u32 s21, s19, 0
	s_add_u32 s22, s20, 0x10000
	s_addc_u32 s23, s21, 0
	s_add_u32 s24, s22, 0x10000
	s_addc_u32 s25, s23, 0
	s_lshl_b32 s59, s58, 11
	s_add_u32 s26, s14, s59
	s_addc_u32 s27, s15, 0
	s_add_u32 s26, s26, 0x2fa0000
	s_addc_u32 s27, s27, 0
	s_add_u32 s28, s26, 0x10000
	s_addc_u32 s29, s27, 0
	s_add_u32 s30, s28, 0x10000
	s_addc_u32 s31, s29, 0
	s_add_u32 s34, s30, 0x10000
	s_addc_u32 s35, s31, 0
	v_readfirstlane_b32 s36, v94
	v_mov_b32_e32 v254, v76
	s_mov_b32 m0, s36
	s_nop 0
	global_load_lds_dwordx4 v254, s[18:19]
	s_add_u32 m0, m0, 0x1000
	s_nop 0
	global_load_lds_dwordx4 v254, s[20:21]
	s_add_u32 m0, m0, 0x1000
	s_nop 0
	global_load_lds_dwordx4 v254, s[22:23]
	s_add_u32 m0, m0, 0x1000
	s_nop 0
	global_load_lds_dwordx4 v254, s[24:25]
	s_add_u32 m0, m0, 0x1000
	s_nop 0
	global_load_lds_dwordx4 v254, s[26:27]
	s_add_u32 m0, m0, 0x1000
	s_nop 0
	global_load_lds_dwordx4 v254, s[28:29]
	s_add_u32 m0, m0, 0x1000
	s_nop 0
	global_load_lds_dwordx4 v254, s[30:31]
	s_add_u32 m0, m0, 0x1000
	s_nop 0
	global_load_lds_dwordx4 v254, s[34:35]
	v_add_u32_e32 v254, 0x80, v254
	s_add_u32 m0, s36, 0x8000
	s_nop 0
	global_load_lds_dwordx4 v254, s[18:19]
	s_add_u32 m0, m0, 0x1000
	s_nop 0
	global_load_lds_dwordx4 v254, s[20:21]
	s_add_u32 m0, m0, 0x1000
	s_nop 0
	global_load_lds_dwordx4 v254, s[22:23]
	s_add_u32 m0, m0, 0x1000
	s_nop 0
	global_load_lds_dwordx4 v254, s[24:25]
	s_add_u32 m0, m0, 0x1000
	s_nop 0
	global_load_lds_dwordx4 v254, s[26:27]
	s_add_u32 m0, m0, 0x1000
	s_nop 0
	global_load_lds_dwordx4 v254, s[28:29]
	s_add_u32 m0, m0, 0x1000
	s_nop 0
	global_load_lds_dwordx4 v254, s[30:31]
	s_add_u32 m0, m0, 0x1000
	s_nop 0
	global_load_lds_dwordx4 v254, s[34:35]
	v_add_u32_e32 v254, 0x80, v254
	v_mov_b32_e32 v48, 0
	v_mov_b32_e32 v49, 0
	v_mov_b32_e32 v50, 0
	v_mov_b32_e32 v51, 0
	v_mov_b32_e32 v52, 0
	v_mov_b32_e32 v53, 0
	v_mov_b32_e32 v54, 0
	v_mov_b32_e32 v55, 0
	v_mov_b32_e32 v56, 0
	v_mov_b32_e32 v57, 0
	v_mov_b32_e32 v58, 0
	v_mov_b32_e32 v59, 0
	v_mov_b32_e32 v60, 0
	v_mov_b32_e32 v61, 0
	v_mov_b32_e32 v62, 0
	v_mov_b32_e32 v63, 0
	v_mov_b32_e32 v32, 0
	v_mov_b32_e32 v33, 0
	v_mov_b32_e32 v34, 0
	v_mov_b32_e32 v35, 0
	v_mov_b32_e32 v36, 0
	v_mov_b32_e32 v37, 0
	v_mov_b32_e32 v38, 0
	v_mov_b32_e32 v39, 0
	v_mov_b32_e32 v40, 0
	v_mov_b32_e32 v41, 0
	v_mov_b32_e32 v42, 0
	v_mov_b32_e32 v43, 0
	v_mov_b32_e32 v44, 0
	v_mov_b32_e32 v45, 0
	v_mov_b32_e32 v46, 0
	v_mov_b32_e32 v47, 0
	v_mov_b32_e32 v16, 0
	v_mov_b32_e32 v17, 0
	v_mov_b32_e32 v18, 0
	v_mov_b32_e32 v19, 0
	v_mov_b32_e32 v20, 0
	v_mov_b32_e32 v21, 0
	v_mov_b32_e32 v22, 0
	v_mov_b32_e32 v23, 0
	v_mov_b32_e32 v24, 0
	v_mov_b32_e32 v25, 0
	v_mov_b32_e32 v26, 0
	v_mov_b32_e32 v27, 0
	v_mov_b32_e32 v28, 0
	v_mov_b32_e32 v29, 0
	v_mov_b32_e32 v30, 0
	v_mov_b32_e32 v31, 0
	v_mov_b32_e32 v0, 0
	v_mov_b32_e32 v1, 0
	v_mov_b32_e32 v2, 0
	v_mov_b32_e32 v3, 0
	v_mov_b32_e32 v4, 0
	v_mov_b32_e32 v5, 0
	v_mov_b32_e32 v6, 0
	v_mov_b32_e32 v7, 0
	v_mov_b32_e32 v8, 0
	v_mov_b32_e32 v9, 0
	v_mov_b32_e32 v10, 0
	v_mov_b32_e32 v11, 0
	v_mov_b32_e32 v12, 0
	v_mov_b32_e32 v13, 0
	v_mov_b32_e32 v14, 0
	v_mov_b32_e32 v15, 0
	s_mov_b32 s37, 7

.Lmap_done_3:
	s_lshl_b32 s60, s4, 7
	s_lshl_b32 s58, s76, 7
	s_ashr_i32 s61, s60, 31
	s_ashr_i32 s59, s58, 31
	s_lshl_b64 s[62:63], s[60:61], 11
	s_lshl_b64 s[64:65], s[58:59], 11
	s_lshl_b32 s59, s60, 11
	s_add_u32 s18, s14, s59
	s_addc_u32 s19, s15, 0
	s_add_u32 s18, s18, 0x679f000
	s_addc_u32 s19, s19, 0
	s_add_u32 s20, s18, 0x10000
	s_addc_u32 s21, s19, 0
	s_add_u32 s22, s20, 0x10000
	s_addc_u32 s23, s21, 0
	s_add_u32 s24, s22, 0x10000
	s_addc_u32 s25, s23, 0
	s_lshl_b32 s59, s58, 11
	s_add_u32 s26, s14, s59
	s_addc_u32 s27, s15, 0
	s_add_u32 s26, s26, 0x3aa0000
	s_addc_u32 s27, s27, 0
	s_add_u32 s28, s26, 0x10000
	s_addc_u32 s29, s27, 0
	s_add_u32 s30, s28, 0x10000
	s_addc_u32 s31, s29, 0
	s_add_u32 s34, s30, 0x10000
	s_addc_u32 s35, s31, 0
	v_readfirstlane_b32 s36, v94
	v_mov_b32_e32 v254, v76
	s_mov_b32 m0, s36
	s_nop 0
	global_load_lds_dwordx4 v254, s[18:19]
	s_add_u32 m0, m0, 0x1000
	s_nop 0
	global_load_lds_dwordx4 v254, s[20:21]
	s_add_u32 m0, m0, 0x1000
	s_nop 0
	global_load_lds_dwordx4 v254, s[22:23]
	s_add_u32 m0, m0, 0x1000
	s_nop 0
	global_load_lds_dwordx4 v254, s[24:25]
	s_add_u32 m0, m0, 0x1000
	s_nop 0
	global_load_lds_dwordx4 v254, s[26:27]
	s_add_u32 m0, m0, 0x1000
	s_nop 0
	global_load_lds_dwordx4 v254, s[28:29]
	s_add_u32 m0, m0, 0x1000
	s_nop 0
	global_load_lds_dwordx4 v254, s[30:31]
	s_add_u32 m0, m0, 0x1000
	s_nop 0
	global_load_lds_dwordx4 v254, s[34:35]
	v_add_u32_e32 v254, 0x80, v254
	s_add_u32 m0, s36, 0x8000
	s_nop 0
	global_load_lds_dwordx4 v254, s[18:19]
	s_add_u32 m0, m0, 0x1000
	s_nop 0
	global_load_lds_dwordx4 v254, s[20:21]
	s_add_u32 m0, m0, 0x1000
	s_nop 0
	global_load_lds_dwordx4 v254, s[22:23]
	s_add_u32 m0, m0, 0x1000
	s_nop 0
	global_load_lds_dwordx4 v254, s[24:25]
	s_add_u32 m0, m0, 0x1000
	s_nop 0
	global_load_lds_dwordx4 v254, s[26:27]
	s_add_u32 m0, m0, 0x1000
	s_nop 0
	global_load_lds_dwordx4 v254, s[28:29]
	s_add_u32 m0, m0, 0x1000
	s_nop 0
	global_load_lds_dwordx4 v254, s[30:31]
	s_add_u32 m0, m0, 0x1000
	s_nop 0
	global_load_lds_dwordx4 v254, s[34:35]
	v_add_u32_e32 v254, 0x80, v254
	v_mov_b32_e32 v48, 0
	v_mov_b32_e32 v49, 0
	v_mov_b32_e32 v50, 0
	v_mov_b32_e32 v51, 0
	v_mov_b32_e32 v52, 0
	v_mov_b32_e32 v53, 0
	v_mov_b32_e32 v54, 0
	v_mov_b32_e32 v55, 0
	v_mov_b32_e32 v56, 0
	v_mov_b32_e32 v57, 0
	v_mov_b32_e32 v58, 0
	v_mov_b32_e32 v59, 0
	v_mov_b32_e32 v60, 0
	v_mov_b32_e32 v61, 0
	v_mov_b32_e32 v62, 0
	v_mov_b32_e32 v63, 0
	v_mov_b32_e32 v32, 0
	v_mov_b32_e32 v33, 0
	v_mov_b32_e32 v34, 0
	v_mov_b32_e32 v35, 0
	v_mov_b32_e32 v36, 0
	v_mov_b32_e32 v37, 0
	v_mov_b32_e32 v38, 0
	v_mov_b32_e32 v39, 0
	v_mov_b32_e32 v40, 0
	v_mov_b32_e32 v41, 0
	v_mov_b32_e32 v42, 0
	v_mov_b32_e32 v43, 0
	v_mov_b32_e32 v44, 0
	v_mov_b32_e32 v45, 0
	v_mov_b32_e32 v46, 0
	v_mov_b32_e32 v47, 0
	v_mov_b32_e32 v16, 0
	v_mov_b32_e32 v17, 0
	v_mov_b32_e32 v18, 0
	v_mov_b32_e32 v19, 0
	v_mov_b32_e32 v20, 0
	v_mov_b32_e32 v21, 0
	v_mov_b32_e32 v22, 0
	v_mov_b32_e32 v23, 0
	v_mov_b32_e32 v24, 0
	v_mov_b32_e32 v25, 0
	v_mov_b32_e32 v26, 0
	v_mov_b32_e32 v27, 0
	v_mov_b32_e32 v28, 0
	v_mov_b32_e32 v29, 0
	v_mov_b32_e32 v30, 0
	v_mov_b32_e32 v31, 0
	v_mov_b32_e32 v0, 0
	v_mov_b32_e32 v1, 0
	v_mov_b32_e32 v2, 0
	v_mov_b32_e32 v3, 0
	v_mov_b32_e32 v4, 0
	v_mov_b32_e32 v5, 0
	v_mov_b32_e32 v6, 0
	v_mov_b32_e32 v7, 0
	v_mov_b32_e32 v8, 0
	v_mov_b32_e32 v9, 0
	v_mov_b32_e32 v10, 0
	v_mov_b32_e32 v11, 0
	v_mov_b32_e32 v12, 0
	v_mov_b32_e32 v13, 0
	v_mov_b32_e32 v14, 0
	v_mov_b32_e32 v15, 0
	s_mov_b32 s37, 7

	.amdhsa_kernel _Z4mega5KArgs
		.amdhsa_group_segment_fixed_size 0
		.amdhsa_private_segment_fixed_size 0
		.amdhsa_kernarg_size 592
		.amdhsa_user_sgpr_count 2
		.amdhsa_user_sgpr_dispatch_ptr 0
		.amdhsa_user_sgpr_queue_ptr 0
		.amdhsa_user_sgpr_kernarg_segment_ptr 1
		.amdhsa_user_sgpr_dispatch_id 0
		.amdhsa_user_sgpr_kernarg_preload_length 0
		.amdhsa_user_sgpr_kernarg_preload_offset 0
		.amdhsa_user_sgpr_private_segment_size 0
		.amdhsa_uses_dynamic_stack 0
		.amdhsa_enable_private_segment 0
		.amdhsa_system_sgpr_workgroup_id_x 1
		.amdhsa_system_sgpr_workgroup_id_y 0
		.amdhsa_system_sgpr_workgroup_id_z 0
		.amdhsa_system_sgpr_workgroup_info 0
		.amdhsa_system_vgpr_workitem_id 2
		.amdhsa_next_free_vgpr 256
		.amdhsa_next_free_sgpr 98
		.amdhsa_accum_offset 256
		.amdhsa_reserve_vcc 1
		.amdhsa_float_round_mode_32 0
		.amdhsa_float_round_mode_16_64 0
		.amdhsa_float_denorm_mode_32 3
		.amdhsa_float_denorm_mode_16_64 3
		.amdhsa_dx10_clamp 1
		.amdhsa_ieee_mode 1
		.amdhsa_fp16_overflow 0
		.amdhsa_tg_split 0
		.amdhsa_exception_fp_ieee_invalid_op 0
		.amdhsa_exception_fp_denorm_src 0
		.amdhsa_exception_fp_ieee_div_zero 0
		.amdhsa_exception_fp_ieee_overflow 0
		.amdhsa_exception_fp_ieee_underflow 0
		.amdhsa_exception_fp_ieee_inexact 0
		.amdhsa_exception_int_div_zero 0
	.end_amdhsa_kernel

amdhsa.kernels:
  - .agpr_count:     0
    .args:
      - .offset:         0
        .size:           336
        .value_kind:     by_value
      - .offset:         336
        .size:           4
        .value_kind:     hidden_block_count_x
      - .offset:         340
        .size:           4
        .value_kind:     hidden_block_count_y
      - .offset:         344
        .size:           4
        .value_kind:     hidden_block_count_z
      - .offset:         348
        .size:           2
        .value_kind:     hidden_group_size_x
      - .offset:         350
        .size:           2
        .value_kind:     hidden_group_size_y
      - .offset:         352
        .size:           2
        .value_kind:     hidden_group_size_z
      - .offset:         354
        .size:           2
        .value_kind:     hidden_remainder_x
      - .offset:         356
        .size:           2
        .value_kind:     hidden_remainder_y
      - .offset:         358
        .size:           2
        .value_kind:     hidden_remainder_z
      - .offset:         376
        .size:           8
        .value_kind:     hidden_global_offset_x
      - .offset:         384
        .size:           8
        .value_kind:     hidden_global_offset_y
      - .offset:         392
        .size:           8
        .value_kind:     hidden_global_offset_z
      - .offset:         400
        .size:           2
        .value_kind:     hidden_grid_dims
      - .offset:         424
        .size:           8
        .value_kind:     hidden_multigrid_sync_arg
      - .offset:         456
        .size:           4
        .value_kind:     hidden_dynamic_lds_size
    .group_segment_fixed_size: 0
    .kernarg_segment_align: 8
    .kernarg_segment_size: 592
    .language:       OpenCL C
    .language_version:
      - 2
      - 0
    .max_flat_workgroup_size: 256
    .name:           _Z4mega5KArgs
    .private_segment_fixed_size: 0
    .sgpr_count:     104
    .sgpr_spill_count: 2
    .symbol:         _Z4mega5KArgs.kd
    .uniform_work_group_size: 1
    .uses_dynamic_stack: false
    .vgpr_count:     256
    .vgpr_spill_count: 0
    .wavefront_size: 64
